# down-projection epilogue: f32 output dwordx4 stores write-through (sc1)
# speedup vs baseline: 1.0092x; 1.0092x over previous
; #define PG8_STAGE(bufoff, gbase, voff) do { _Pragma("unroll") for (int _i = 0; _i < 2; ++_i) \
;         __builtin_amdgcn_global_load_lds((const unsigned*)((const char*)(gbase) + (voff)[_i]), (LAS unsigned*)(lds + (bufoff) + ldsw + _i * 8192), 16, 0, 0); } while (0)
; #define PG8_LDA(dst, b, h) do { _Pragma("unroll") for (int m = 0; m < 4; ++m) _Pragma("unroll") for (int k = 0; k < 2; ++k) dst[m][k] = *(const LAS bf16x8*)(lds + PG8_SA(b, h) + aoff + m * 2048 + k * 1024); } while (0)
; #define PG8_LDB(dst, b, h) do { _Pragma("unroll") for (int n = 0; n < 2; ++n) _Pragma("unroll") for (int k = 0; k < 2; ++k) dst[n][k] = *(const LAS bf16x8*)(lds + PG8_SB(b, h) + boff + n * 2048 + k * 1024); } while (0)
; #define PG8_WAIT_V(n) asm volatile("s_waitcnt vmcnt(" #n ")" ::: "memory")
; #define PG8_WAIT_L(n) asm volatile("s_waitcnt lgkmcnt(" #n ")" ::: "memory")
; #define PG8_BAR __builtin_amdgcn_s_barrier()
; #define PG8_SCHED __builtin_amdgcn_sched_barrier(0)
; template <class Epi, class Sched>
; __device__ __forceinline__ void gemm_phase(LAS unsigned char* lds, const int K, const Sched& S, const Epi& E) {
;     ...
;         for (int t = 0; t < nt; t += 2) {
;             const bool last = (t == nt - 2);
;             const char* a1 = cA + (size_t)(t + 1) * kstep;
;             const char* a2 = last ? nA : cA + (size_t)(t + 2) * kstep; const char* b2 = last ? nB : cB + (size_t)(t + 2) * kstep;
;             const char* a3 = a2 + kstep; const char* b3 = b2 + kstep;
;             PG8_LDB(B0, 0, 0); PG8_SCHED; PG8_LDA(At, 0, 0); PG8_STAGE(PG8_SA(1, 1), a1 + hstepA, voffA);
;             PG8_WAIT_L(8); PG8_BAR; PG8_WAIT_L(0); PG8_MMA(0, 0, At, B0); PG8_BAR; PG8_SCHED;
;             PG8_LDB(B1, 0, 1); PG8_STAGE(PG8_SB(0, 0), b2, voffB);
;             PG8_BAR; PG8_WAIT_L(0); PG8_MMA(0, 1, At, B1); PG8_BAR;
;             PG8_LDA(At, 0, 1); PG8_STAGE(PG8_SA(0, 0), a2, voffA);
;             PG8_BAR; PG8_WAIT_L(0); PG8_MMA(1, 0, At, B0); PG8_BAR; PG8_SCHED;
;             PG8_STAGE(PG8_SB(0, 1), b2 + hstep, voffB);
;             PG8_WAIT_V(6); PG8_BAR; PG8_MMA(1, 1, At, B1); PG8_BAR;
;             PG8_LDB(B0, 1, 0); PG8_SCHED; PG8_LDA(At, 1, 0); PG8_STAGE(PG8_SA(0, 1), a2 + hstepA, voffA);
;             PG8_WAIT_L(8); PG8_BAR; PG8_WAIT_L(0); PG8_MMA(0, 0, At, B0); PG8_BAR; PG8_SCHED;
.LBB0_1081:
	ds_read_b128 v[96:99], v165
	ds_read_b128 v[100:103], v165 offset:1024
	ds_read_b128 v[104:107], v165 offset:2048
	ds_read_b128 v[112:115], v165 offset:3072
	s_add_u32 s24, s22, 0xfff50080
	s_addc_u32 s25, s23, -1
	s_cmp_eq_u32 s52, 40
	s_cselect_b32 s27, s19, s25
	s_cselect_b32 s26, s18, s24
	s_cselect_b32 s25, s21, s33
	s_cselect_b32 s24, s20, s11
	s_mov_b32 m0, s51
	v_lshl_add_u64 v[200:201], s[22:23], 0, v[148:149]
	ds_read_b128 v[152:155], v166
	ds_read_b128 v[172:175], v166 offset:1024
	ds_read_b128 v[176:179], v166 offset:2048
	ds_read_b128 v[180:183], v166 offset:3072
	ds_read_b128 v[184:187], v166 offset:4096
	ds_read_b128 v[188:191], v166 offset:5120
	ds_read_b128 v[192:195], v166 offset:6144
	ds_read_b128 v[196:199], v166 offset:7168
	global_load_lds_dwordx4 v[200:201], off
	v_lshl_add_u64 v[200:201], s[22:23], 0, v[150:151]
	s_mov_b32 m0, s58
	s_nop 0
	global_load_lds_dwordx4 v[200:201], off
	s_waitcnt lgkmcnt(8)
	s_barrier
	s_waitcnt lgkmcnt(0)
	s_setprio 1
	s_waitcnt lgkmcnt(0)
	v_mfma_f32_16x16x32_bf16 v[140:143], v[96:99], v[152:155], v[140:143]
	v_mfma_f32_16x16x32_bf16 v[136:139], v[104:107], v[152:155], v[136:139]
	v_mfma_f32_16x16x32_bf16 v[124:127], v[96:99], v[176:179], v[124:127]
	v_mfma_f32_16x16x32_bf16 v[120:123], v[104:107], v[176:179], v[120:123]
	v_mfma_f32_16x16x32_bf16 v[92:95], v[96:99], v[184:187], v[92:95]
	v_mfma_f32_16x16x32_bf16 v[88:91], v[104:107], v[184:187], v[88:91]
	v_mfma_f32_16x16x32_bf16 v[76:79], v[96:99], v[192:195], v[76:79]
	v_mfma_f32_16x16x32_bf16 v[72:75], v[104:107], v[192:195], v[72:75]
	v_mfma_f32_16x16x32_bf16 v[140:143], v[100:103], v[172:175], v[140:143]
	v_mfma_f32_16x16x32_bf16 v[136:139], v[112:115], v[172:175], v[136:139]
	v_mfma_f32_16x16x32_bf16 v[124:127], v[100:103], v[180:183], v[124:127]
	v_mfma_f32_16x16x32_bf16 v[120:123], v[112:115], v[180:183], v[120:123]
	v_mfma_f32_16x16x32_bf16 v[92:95], v[100:103], v[188:191], v[92:95]
	v_mfma_f32_16x16x32_bf16 v[88:91], v[112:115], v[188:191], v[88:91]
	v_mfma_f32_16x16x32_bf16 v[76:79], v[100:103], v[196:199], v[76:79]
	v_mfma_f32_16x16x32_bf16 v[72:75], v[112:115], v[196:199], v[72:75]
	s_setprio 0
	s_barrier
	s_mov_b32 m0, s59
	v_lshl_add_u64 v[216:217], s[24:25], 0, v[144:145]
	ds_read_b128 v[200:203], v167
	ds_read_b128 v[204:207], v167 offset:1024
	ds_read_b128 v[208:211], v167 offset:2048
	ds_read_b128 v[212:215], v167 offset:3072
	global_load_lds_dwordx4 v[216:217], off
	v_lshl_add_u64 v[218:219], s[24:25], 0, v[146:147]
	s_mov_b32 m0, s60
	s_nop 0
	global_load_lds_dwordx4 v[218:219], off
	s_barrier
	s_waitcnt lgkmcnt(0)
	s_setprio 1
	s_waitcnt lgkmcnt(0)
	v_mfma_f32_16x16x32_bf16 v[132:135], v[200:203], v[152:155], v[132:135]
	v_mfma_f32_16x16x32_bf16 v[128:131], v[208:211], v[152:155], v[128:131]
	v_mfma_f32_16x16x32_bf16 v[116:119], v[200:203], v[176:179], v[116:119]
	v_mfma_f32_16x16x32_bf16 v[108:111], v[208:211], v[176:179], v[108:111]
	v_mfma_f32_16x16x32_bf16 v[84:87], v[200:203], v[184:187], v[84:87]
	v_mfma_f32_16x16x32_bf16 v[80:83], v[208:211], v[184:187], v[80:83]
	v_mfma_f32_16x16x32_bf16 v[68:71], v[200:203], v[192:195], v[68:71]
	v_mfma_f32_16x16x32_bf16 v[64:67], v[208:211], v[192:195], v[64:67]
	v_mfma_f32_16x16x32_bf16 v[132:135], v[204:207], v[172:175], v[132:135]
	v_mfma_f32_16x16x32_bf16 v[128:131], v[212:215], v[172:175], v[128:131]
	v_mfma_f32_16x16x32_bf16 v[116:119], v[204:207], v[180:183], v[116:119]
	v_mfma_f32_16x16x32_bf16 v[108:111], v[212:215], v[180:183], v[108:111]
	v_mfma_f32_16x16x32_bf16 v[84:87], v[204:207], v[188:191], v[84:87]
	v_mfma_f32_16x16x32_bf16 v[80:83], v[212:215], v[188:191], v[80:83]
	v_mfma_f32_16x16x32_bf16 v[68:71], v[204:207], v[196:199], v[68:71]
	v_mfma_f32_16x16x32_bf16 v[64:67], v[212:215], v[196:199], v[64:67]
	s_setprio 0
	s_mov_b32 m0, s42
	v_lshl_add_u64 v[220:221], s[26:27], 0, v[144:145]
	s_barrier
	ds_read_b128 v[152:155], v166 offset:16384
	ds_read_b128 v[172:175], v166 offset:17408
	ds_read_b128 v[176:179], v166 offset:18432
	ds_read_b128 v[180:183], v166 offset:19456
	ds_read_b128 v[184:187], v166 offset:20480
	ds_read_b128 v[188:191], v166 offset:21504
	ds_read_b128 v[192:195], v166 offset:22528
	ds_read_b128 v[196:199], v166 offset:23552
	global_load_lds_dwordx4 v[220:221], off
	v_lshl_add_u64 v[222:223], s[26:27], 0, v[146:147]
	s_mov_b32 m0, s43
	s_nop 0
	global_load_lds_dwordx4 v[222:223], off
	s_barrier
	s_waitcnt lgkmcnt(0)
	s_setprio 1
	s_waitcnt lgkmcnt(0)
	v_mfma_f32_16x16x32_bf16 v[60:63], v[96:99], v[152:155], v[60:63]
	v_mfma_f32_16x16x32_bf16 v[56:59], v[104:107], v[152:155], v[56:59]
	v_mfma_f32_16x16x32_bf16 v[44:47], v[96:99], v[176:179], v[44:47]
	v_mfma_f32_16x16x32_bf16 v[40:43], v[104:107], v[176:179], v[40:43]
	v_mfma_f32_16x16x32_bf16 v[28:31], v[96:99], v[184:187], v[28:31]
	v_mfma_f32_16x16x32_bf16 v[24:27], v[104:107], v[184:187], v[24:27]
	v_mfma_f32_16x16x32_bf16 v[12:15], v[96:99], v[192:195], v[12:15]
	v_mfma_f32_16x16x32_bf16 v[8:11], v[104:107], v[192:195], v[8:11]
	v_mfma_f32_16x16x32_bf16 v[60:63], v[100:103], v[172:175], v[60:63]
	v_mfma_f32_16x16x32_bf16 v[56:59], v[112:115], v[172:175], v[56:59]
	v_mfma_f32_16x16x32_bf16 v[44:47], v[100:103], v[180:183], v[44:47]
	v_mfma_f32_16x16x32_bf16 v[40:43], v[112:115], v[180:183], v[40:43]
	v_mfma_f32_16x16x32_bf16 v[28:31], v[100:103], v[188:191], v[28:31]
	v_mfma_f32_16x16x32_bf16 v[24:27], v[112:115], v[188:191], v[24:27]
	v_mfma_f32_16x16x32_bf16 v[12:15], v[100:103], v[196:199], v[12:15]
	v_mfma_f32_16x16x32_bf16 v[8:11], v[112:115], v[196:199], v[8:11]
	s_setprio 0
	s_barrier
; #define PG8_STAGE(bufoff, gbase, voff) do { _Pragma("unroll") for (int _i = 0; _i < 2; ++_i) \
;         __builtin_amdgcn_global_load_lds((const unsigned*)((const char*)(gbase) + (voff)[_i]), (LAS unsigned*)(lds + (bufoff) + ldsw + _i * 8192), 16, 0, 0); } while (0)
; #define PG8_LDA(dst, b, h) do { _Pragma("unroll") for (int m = 0; m < 4; ++m) _Pragma("unroll") for (int k = 0; k < 2; ++k) dst[m][k] = *(const LAS bf16x8*)(lds + PG8_SA(b, h) + aoff + m * 2048 + k * 1024); } while (0)
; #define PG8_LDB(dst, b, h) do { _Pragma("unroll") for (int n = 0; n < 2; ++n) _Pragma("unroll") for (int k = 0; k < 2; ++k) dst[n][k] = *(const LAS bf16x8*)(lds + PG8_SB(b, h) + boff + n * 2048 + k * 1024); } while (0)
; #define PG8_MMA(ai, bj, At, Bt) do { __builtin_amdgcn_s_setprio(1); _Pragma("unroll") for (int m = 0; m < 4; ++m) _Pragma("unroll") for (int n = 0; n < 2; ++n) _Pragma("unroll") for (int k = 0; k < 2; ++k) \
;         acc[ai][bj][m][n] = __builtin_amdgcn_mfma_f32_16x16x32_bf16(Bt[n][k], At[m][k], acc[ai][bj][m][n], 0, 0, 0); __builtin_amdgcn_s_setprio(0); } while (0)
; #define PG8_WAIT_V(n) asm volatile("s_waitcnt vmcnt(" #n ")" ::: "memory")
; #define PG8_WAIT_L(n) asm volatile("s_waitcnt lgkmcnt(" #n ")" ::: "memory")
; #define PG8_BAR __builtin_amdgcn_s_barrier()
; #define PG8_SCHED __builtin_amdgcn_sched_barrier(0)
; template <class Epi, class Sched>
; __device__ __forceinline__ void gemm_phase(LAS unsigned char* lds, const int K, const Sched& S, const Epi& E) {
;     ...
;             PG8_STAGE(PG8_SB(0, 1), b2 + hstep, voffB);
;             PG8_WAIT_V(6); PG8_BAR; PG8_MMA(1, 1, At, B1); PG8_BAR;
;             PG8_LDB(B0, 1, 0); PG8_SCHED; PG8_LDA(At, 1, 0); PG8_STAGE(PG8_SA(0, 1), a2 + hstepA, voffA);
;             PG8_WAIT_L(8); PG8_BAR; PG8_WAIT_L(0); PG8_MMA(0, 0, At, B0); PG8_BAR; PG8_SCHED;
;             PG8_LDB(B1, 1, 1); PG8_STAGE(PG8_SB(1, 0), b3, voffB);
;             PG8_BAR; PG8_WAIT_L(0); PG8_MMA(0, 1, At, B1); PG8_BAR;
;             PG8_LDA(At, 1, 1); PG8_STAGE(PG8_SA(1, 0), a3, voffA);
;             PG8_BAR; PG8_WAIT_L(0); PG8_MMA(1, 0, At, B0); PG8_BAR; PG8_SCHED;
;             PG8_STAGE(PG8_SB(1, 1), b3 + hstep, voffB);
	s_add_u32 s54, s24, 0xb0000
	s_addc_u32 s55, s25, 0
	s_mov_b32 m0, s61
	v_lshl_add_u64 v[96:97], s[54:55], 0, v[144:145]
	global_load_lds_dwordx4 v[96:97], off
	v_lshl_add_u64 v[96:97], s[54:55], 0, v[146:147]
	s_mov_b32 m0, s62
	s_nop 0
	global_load_lds_dwordx4 v[96:97], off
	s_waitcnt vmcnt(6)
	s_barrier
	s_setprio 1
	v_mfma_f32_16x16x32_bf16 v[52:55], v[200:203], v[152:155], v[52:55]
	v_mfma_f32_16x16x32_bf16 v[48:51], v[208:211], v[152:155], v[48:51]
	v_mfma_f32_16x16x32_bf16 v[36:39], v[200:203], v[176:179], v[36:39]
	v_mfma_f32_16x16x32_bf16 v[32:35], v[208:211], v[176:179], v[32:35]
	v_mfma_f32_16x16x32_bf16 v[20:23], v[200:203], v[184:187], v[20:23]
	v_mfma_f32_16x16x32_bf16 v[16:19], v[208:211], v[184:187], v[16:19]
	v_mfma_f32_16x16x32_bf16 v[4:7], v[200:203], v[192:195], v[4:7]
	v_mfma_f32_16x16x32_bf16 v[0:3], v[208:211], v[192:195], v[0:3]
	v_mfma_f32_16x16x32_bf16 v[52:55], v[204:207], v[172:175], v[52:55]
	v_mfma_f32_16x16x32_bf16 v[48:51], v[212:215], v[172:175], v[48:51]
	v_mfma_f32_16x16x32_bf16 v[36:39], v[204:207], v[180:183], v[36:39]
	v_mfma_f32_16x16x32_bf16 v[32:35], v[212:215], v[180:183], v[32:35]
	v_mfma_f32_16x16x32_bf16 v[20:23], v[204:207], v[188:191], v[20:23]
	v_mfma_f32_16x16x32_bf16 v[16:19], v[212:215], v[188:191], v[16:19]
	v_mfma_f32_16x16x32_bf16 v[4:7], v[204:207], v[196:199], v[4:7]
	v_mfma_f32_16x16x32_bf16 v[0:3], v[212:215], v[196:199], v[0:3]
	s_setprio 0
	s_add_i32 s53, 0, 0x18000
	v_add_u32_e32 v112, s53, v163
	s_barrier
	ds_read_b128 v[96:99], v112
	ds_read_b128 v[100:103], v112 offset:1024
	ds_read_b128 v[104:107], v112 offset:2048
	ds_read_b128 v[112:115], v112 offset:3072
	s_add_u32 s26, s26, 0xb0000
	s_addc_u32 s27, s27, 0
	s_mov_b32 m0, s44
	v_lshl_add_u64 v[200:201], s[26:27], 0, v[144:145]
	ds_read_b128 v[152:155], v166 offset:32768
	ds_read_b128 v[172:175], v166 offset:33792
	ds_read_b128 v[176:179], v166 offset:34816
	ds_read_b128 v[180:183], v166 offset:35840
	ds_read_b128 v[184:187], v166 offset:36864
	ds_read_b128 v[188:191], v166 offset:37888
	ds_read_b128 v[192:195], v166 offset:38912
	ds_read_b128 v[196:199], v166 offset:39936
	global_load_lds_dwordx4 v[200:201], off
	v_lshl_add_u64 v[200:201], s[26:27], 0, v[146:147]
	s_mov_b32 m0, s45
	s_nop 0
	global_load_lds_dwordx4 v[200:201], off
	s_waitcnt lgkmcnt(8)
	s_barrier
	s_waitcnt lgkmcnt(0)
	s_setprio 1
	s_waitcnt lgkmcnt(0)
	v_mfma_f32_16x16x32_bf16 v[140:143], v[96:99], v[152:155], v[140:143]
	v_mfma_f32_16x16x32_bf16 v[136:139], v[104:107], v[152:155], v[136:139]
	v_mfma_f32_16x16x32_bf16 v[124:127], v[96:99], v[176:179], v[124:127]
	v_mfma_f32_16x16x32_bf16 v[120:123], v[104:107], v[176:179], v[120:123]
	v_mfma_f32_16x16x32_bf16 v[92:95], v[96:99], v[184:187], v[92:95]
	v_mfma_f32_16x16x32_bf16 v[88:91], v[104:107], v[184:187], v[88:91]
	v_mfma_f32_16x16x32_bf16 v[76:79], v[96:99], v[192:195], v[76:79]
	v_mfma_f32_16x16x32_bf16 v[72:75], v[104:107], v[192:195], v[72:75]
	v_mfma_f32_16x16x32_bf16 v[140:143], v[100:103], v[172:175], v[140:143]
	v_mfma_f32_16x16x32_bf16 v[136:139], v[112:115], v[172:175], v[136:139]
	v_mfma_f32_16x16x32_bf16 v[124:127], v[100:103], v[180:183], v[124:127]
	v_mfma_f32_16x16x32_bf16 v[120:123], v[112:115], v[180:183], v[120:123]
	v_mfma_f32_16x16x32_bf16 v[92:95], v[100:103], v[188:191], v[92:95]
	v_mfma_f32_16x16x32_bf16 v[88:91], v[112:115], v[188:191], v[88:91]
	v_mfma_f32_16x16x32_bf16 v[76:79], v[100:103], v[196:199], v[76:79]
	v_mfma_f32_16x16x32_bf16 v[72:75], v[112:115], v[196:199], v[72:75]
	s_setprio 0
	s_barrier
	s_add_i32 s26, 0, 0x1c000
	s_add_i32 s27, s53, s37
	v_add_u32_e32 v169, s26, v163
	v_lshl_add_u64 v[216:217], v[216:217], 0, s[12:13]
	s_mov_b32 m0, s27
	ds_read_b128 v[200:203], v169
	ds_read_b128 v[204:207], v169 offset:1024
	ds_read_b128 v[208:211], v169 offset:2048
	ds_read_b128 v[212:215], v169 offset:3072
	global_load_lds_dwordx4 v[216:217], off
	v_lshl_add_u64 v[216:217], v[218:219], 0, s[12:13]
	s_add_i32 m0, s27, 0x2000
	s_nop 0
	global_load_lds_dwordx4 v[216:217], off
	s_barrier
	s_waitcnt lgkmcnt(0)
	s_setprio 1
	s_waitcnt lgkmcnt(0)
	v_mfma_f32_16x16x32_bf16 v[132:135], v[200:203], v[152:155], v[132:135]
	v_mfma_f32_16x16x32_bf16 v[128:131], v[208:211], v[152:155], v[128:131]
	v_mfma_f32_16x16x32_bf16 v[116:119], v[200:203], v[176:179], v[116:119]
	v_mfma_f32_16x16x32_bf16 v[108:111], v[208:211], v[176:179], v[108:111]
	v_mfma_f32_16x16x32_bf16 v[84:87], v[200:203], v[184:187], v[84:87]
	v_mfma_f32_16x16x32_bf16 v[80:83], v[208:211], v[184:187], v[80:83]
	v_mfma_f32_16x16x32_bf16 v[68:71], v[200:203], v[192:195], v[68:71]
	v_mfma_f32_16x16x32_bf16 v[64:67], v[208:211], v[192:195], v[64:67]
	v_mfma_f32_16x16x32_bf16 v[132:135], v[204:207], v[172:175], v[132:135]
	v_mfma_f32_16x16x32_bf16 v[128:131], v[212:215], v[172:175], v[128:131]
	v_mfma_f32_16x16x32_bf16 v[116:119], v[204:207], v[180:183], v[116:119]
	v_mfma_f32_16x16x32_bf16 v[108:111], v[212:215], v[180:183], v[108:111]
	v_mfma_f32_16x16x32_bf16 v[84:87], v[204:207], v[188:191], v[84:87]
	v_mfma_f32_16x16x32_bf16 v[80:83], v[212:215], v[188:191], v[80:83]
	v_mfma_f32_16x16x32_bf16 v[68:71], v[204:207], v[196:199], v[68:71]
	v_mfma_f32_16x16x32_bf16 v[64:67], v[212:215], v[196:199], v[64:67]
	s_setprio 0
	s_mov_b32 m0, s49
	v_lshl_add_u64 v[216:217], v[220:221], 0, s[12:13]
	s_barrier
	ds_read_b128 v[152:155], v166 offset:49152
	ds_read_b128 v[172:175], v166 offset:50176
	ds_read_b128 v[176:179], v166 offset:51200
	ds_read_b128 v[180:183], v166 offset:52224
	ds_read_b128 v[184:187], v166 offset:53248
	ds_read_b128 v[188:191], v166 offset:54272
	ds_read_b128 v[192:195], v166 offset:55296
	ds_read_b128 v[196:199], v166 offset:56320
	global_load_lds_dwordx4 v[216:217], off
	v_lshl_add_u64 v[216:217], v[222:223], 0, s[12:13]
	s_mov_b32 m0, s50
	s_nop 0
	global_load_lds_dwordx4 v[216:217], off
	s_barrier
; #define PG8_STAGE(bufoff, gbase, voff) do { _Pragma("unroll") for (int _i = 0; _i < 2; ++_i) \
;         __builtin_amdgcn_global_load_lds((const unsigned*)((const char*)(gbase) + (voff)[_i]), (LAS unsigned*)(lds + (bufoff) + ldsw + _i * 8192), 16, 0, 0); } while (0)
; #define PG8_MMA(ai, bj, At, Bt) do { __builtin_amdgcn_s_setprio(1); _Pragma("unroll") for (int m = 0; m < 4; ++m) _Pragma("unroll") for (int n = 0; n < 2; ++n) _Pragma("unroll") for (int k = 0; k < 2; ++k) \
;         acc[ai][bj][m][n] = __builtin_amdgcn_mfma_f32_16x16x32_bf16(Bt[n][k], At[m][k], acc[ai][bj][m][n], 0, 0, 0); __builtin_amdgcn_s_setprio(0); } while (0)
; #define PG8_WAIT_V(n) asm volatile("s_waitcnt vmcnt(" #n ")" ::: "memory")
; #define PG8_BAR __builtin_amdgcn_s_barrier()
; template <class Epi, class Sched>
; __device__ __forceinline__ void gemm_phase(LAS unsigned char* lds, const int K, const Sched& S, const Epi& E) {
;     ...
;             PG8_STAGE(PG8_SB(1, 1), b3 + hstep, voffB);
;             PG8_WAIT_V(6); PG8_BAR; PG8_MMA(1, 1, At, B1); PG8_BAR;
;         }
;     __device__ __forceinline__ void operator()(const f32x4 (&acc)[2][2][4][2], const Unit& u, int wr, int wc, int fr, int fq) const {
;         const int row0 = u.pm * BM + wr * 64 + fr, col0 = u.pn * BM + wc * 32 + 4 * fq, b = u.pm >> 3;
;         f32x4 gv[2][2];
; #pragma unroll
;         for (int bj = 0; bj < 2; ++bj)
; #pragma unroll
;             for (int n = 0; n < 2; ++n) gv[bj][n] = *(const f32x4*)(gate + (size_t)b * NMOD + col0 + bj * HALF + n * 16);
; #pragma unroll
;         for (int ai = 0; ai < 2; ++ai)
; #pragma unroll
;             for (int m = 0; m < 4; ++m) { const int row = row0 + ai * HALF + m * 16; const size_t off = (size_t)row * DM + col0; float s = 0.f;
; #pragma unroll
;                 for (int bj = 0; bj < 2; ++bj)
; #pragma unroll
;                     for (int n = 0; n < 2; ++n) { const f32x4 xv = *(const f32x4*)(base + off + bj * HALF + n * 16); const f32x4 o = xv + gv[bj][n] * acc[ai][bj][m][n];
;                         *(f32x4*)(out + off + bj * HALF + n * 16) = o; s += (o[0] * o[0] + o[1] * o[1]) + (o[2] * o[2] + o[3] * o[3]); }
;                 s += __shfl_xor(s, 16); s += __shfl_xor(s, 32);
;                 if (fq == 0) ssq[(size_t)row * 16 + u.pn * 4 + wc] = s; }
	s_waitcnt lgkmcnt(0)
	s_setprio 1
	s_waitcnt lgkmcnt(0)
	v_mfma_f32_16x16x32_bf16 v[60:63], v[96:99], v[152:155], v[60:63]
	v_mfma_f32_16x16x32_bf16 v[56:59], v[104:107], v[152:155], v[56:59]
	v_mfma_f32_16x16x32_bf16 v[44:47], v[96:99], v[176:179], v[44:47]
	v_mfma_f32_16x16x32_bf16 v[40:43], v[104:107], v[176:179], v[40:43]
	v_mfma_f32_16x16x32_bf16 v[28:31], v[96:99], v[184:187], v[28:31]
	v_mfma_f32_16x16x32_bf16 v[24:27], v[104:107], v[184:187], v[24:27]
	v_mfma_f32_16x16x32_bf16 v[12:15], v[96:99], v[192:195], v[12:15]
	v_mfma_f32_16x16x32_bf16 v[8:11], v[104:107], v[192:195], v[8:11]
	v_mfma_f32_16x16x32_bf16 v[60:63], v[100:103], v[172:175], v[60:63]
	v_mfma_f32_16x16x32_bf16 v[56:59], v[112:115], v[172:175], v[56:59]
	v_mfma_f32_16x16x32_bf16 v[44:47], v[100:103], v[180:183], v[44:47]
	v_mfma_f32_16x16x32_bf16 v[40:43], v[112:115], v[180:183], v[40:43]
	v_mfma_f32_16x16x32_bf16 v[28:31], v[100:103], v[188:191], v[28:31]
	v_mfma_f32_16x16x32_bf16 v[24:27], v[112:115], v[188:191], v[24:27]
	v_mfma_f32_16x16x32_bf16 v[12:15], v[100:103], v[196:199], v[12:15]
	v_mfma_f32_16x16x32_bf16 v[8:11], v[112:115], v[196:199], v[8:11]
	s_setprio 0
	s_barrier
	s_add_u32 s24, s24, 0xb0080
	s_addc_u32 s25, s25, 0
	s_add_i32 s26, s26, s37
	v_lshl_add_u64 v[96:97], s[24:25], 0, v[144:145]
	s_mov_b32 m0, s26
	s_nop 0
	global_load_lds_dwordx4 v[96:97], off
	v_lshl_add_u64 v[96:97], s[24:25], 0, v[146:147]
	s_add_i32 m0, s26, 0x2000
	s_nop 0
	global_load_lds_dwordx4 v[96:97], off
	s_waitcnt vmcnt(6)
	s_barrier
	s_setprio 1
	v_mfma_f32_16x16x32_bf16 v[52:55], v[200:203], v[152:155], v[52:55]
	v_mfma_f32_16x16x32_bf16 v[48:51], v[208:211], v[152:155], v[48:51]
	v_mfma_f32_16x16x32_bf16 v[36:39], v[200:203], v[176:179], v[36:39]
	v_mfma_f32_16x16x32_bf16 v[32:35], v[208:211], v[176:179], v[32:35]
	v_mfma_f32_16x16x32_bf16 v[20:23], v[200:203], v[184:187], v[20:23]
	v_mfma_f32_16x16x32_bf16 v[16:19], v[208:211], v[184:187], v[16:19]
	v_mfma_f32_16x16x32_bf16 v[4:7], v[200:203], v[192:195], v[4:7]
	v_mfma_f32_16x16x32_bf16 v[0:3], v[208:211], v[192:195], v[0:3]
	v_mfma_f32_16x16x32_bf16 v[52:55], v[204:207], v[172:175], v[52:55]
	v_mfma_f32_16x16x32_bf16 v[48:51], v[212:215], v[172:175], v[48:51]
	v_mfma_f32_16x16x32_bf16 v[36:39], v[204:207], v[180:183], v[36:39]
	v_mfma_f32_16x16x32_bf16 v[32:35], v[212:215], v[180:183], v[32:35]
	v_mfma_f32_16x16x32_bf16 v[20:23], v[204:207], v[188:191], v[20:23]
	v_mfma_f32_16x16x32_bf16 v[16:19], v[212:215], v[188:191], v[16:19]
	v_mfma_f32_16x16x32_bf16 v[4:7], v[204:207], v[196:199], v[4:7]
	v_mfma_f32_16x16x32_bf16 v[0:3], v[212:215], v[196:199], v[0:3]
	s_setprio 0
	s_add_i32 s52, s52, 2
	s_add_u32 s22, s22, 0x100
	s_addc_u32 s23, s23, 0
	s_add_u32 s11, s11, 0x100
	s_addc_u32 s33, s33, 0
	s_cmp_gt_u32 s52, 41
	s_barrier
	s_cbranch_scc0 .LBB0_1081
	s_ashr_i32 s11, s10, 3
	v_lshl_add_u32 v154, s10, 8, v162
	v_lshl_or_b32 v152, s8, 8, v164
	s_mul_hi_i32 s23, s11, 0x6000
	s_mulk_i32 s11, 0x6000
	v_ashrrev_i32_e32 v155, 31, v154
	s_add_u32 s22, s46, s11
	v_ashrrev_i32_e32 v153, 31, v152
	v_lshlrev_b64 v[98:99], 12, v[154:155]
	s_addc_u32 s23, s47, s23
	v_lshlrev_b64 v[96:97], 2, v[152:153]
	v_lshl_add_u64 v[98:99], s[30:31], 0, v[98:99]
	v_lshl_add_u64 v[104:105], s[22:23], 0, v[96:97]
	v_lshl_add_u64 v[188:189], v[98:99], 0, v[96:97]
	global_load_dwordx4 v[172:175], v[188:189], off
	global_load_dwordx4 v[100:103], v[104:105], off
	global_load_dwordx4 v[96:99], v[104:105], off offset:64
	global_load_dwordx4 v[176:179], v[188:189], off offset:64
	global_load_dwordx4 v[180:183], v[188:189], off offset:512
	global_load_dwordx4 v[112:115], v[104:105], off offset:512
	s_nop 0
	global_load_dwordx4 v[104:107], v[104:105], off offset:576
	s_nop 0
	global_load_dwordx4 v[184:187], v[188:189], off offset:576
	v_and_b32_e32 v190, 64, v168
	v_xor_b32_e32 v169, 16, v168
	v_add_u32_e32 v190, 64, v190
	v_cmp_lt_i32_e32 vcc, v169, v190
	v_xor_b32_e32 v191, 32, v168
	s_lshl_b32 s22, s8, 2
	v_cndmask_b32_e32 v169, v168, v169, vcc
	v_lshlrev_b32_e32 v169, 2, v169
	v_cmp_lt_i32_e32 vcc, v191, v190
	s_ashr_i32 s23, s22, 31
	s_waitcnt vmcnt(0)
	v_pk_fma_f32 v[142:143], v[142:143], v[102:103], v[174:175]
	v_pk_fma_f32 v[140:141], v[140:141], v[100:101], v[172:173]
	v_pk_fma_f32 v[138:139], v[138:139], v[98:99], v[178:179]
	v_pk_fma_f32 v[136:137], v[136:137], v[96:97], v[176:177]
	v_pk_fma_f32 v[134:135], v[134:135], v[114:115], v[182:183]
	v_pk_fma_f32 v[132:133], v[132:133], v[112:113], v[180:181]
	v_pk_fma_f32 v[174:175], v[130:131], v[106:107], v[186:187]
	v_pk_fma_f32 v[172:173], v[128:129], v[104:105], v[184:185]
	v_mul_f32_e32 v128, v141, v141
	v_mul_f32_e32 v129, v143, v143
	v_mul_f32_e32 v130, v137, v137
	v_mul_f32_e32 v131, v139, v139
	v_mul_f32_e32 v176, v133, v133
	v_mul_f32_e32 v177, v135, v135
	v_fmac_f32_e32 v128, v140, v140
	v_fmac_f32_e32 v129, v142, v142
	v_fmac_f32_e32 v130, v136, v136
	v_fmac_f32_e32 v131, v138, v138
	v_mul_f32_e32 v178, v173, v173
	v_mul_f32_e32 v179, v175, v175
	v_fmac_f32_e32 v176, v132, v132
	v_fmac_f32_e32 v177, v134, v134
	v_add_f32_e32 v128, v128, v129
	v_add_f32_e32 v129, v130, v131
	v_fmac_f32_e32 v178, v172, v172
	v_fmac_f32_e32 v179, v174, v174
	v_add_f32_e32 v130, v176, v177
	v_add_f32_e32 v128, v128, v129
	v_add_f32_e32 v131, v178, v179
	v_add_f32_e32 v128, v128, v130
	v_add_f32_e32 v128, v128, v131
	ds_bpermute_b32 v129, v169, v128
	v_cndmask_b32_e32 v130, v168, v191, vcc
	v_lshlrev_b32_e32 v130, 2, v130
	global_store_dwordx4 v[188:189], v[140:143], off sc1
	global_store_dwordx4 v[188:189], v[136:139], off offset:64 sc1
	global_store_dwordx4 v[188:189], v[132:135], off offset:512 sc1
	global_store_dwordx4 v[188:189], v[172:175], off offset:576 sc1
	s_waitcnt lgkmcnt(0)
	v_add_f32_e32 v128, v128, v129
	ds_bpermute_b32 v129, v130, v128
	s_and_saveexec_b64 s[24:25], s[0:1]
	s_cbranch_execz .LBB0_1084
	v_lshlrev_b64 v[132:133], 6, v[154:155]
	v_lshl_add_u64 v[132:133], s[6:7], 0, v[132:133]
	v_lshl_add_u64 v[132:133], s[22:23], 2, v[132:133]
	s_lshl_b32 s8, s48, 2
	v_lshl_add_u64 v[132:133], v[132:133], 0, s[8:9]
	s_waitcnt lgkmcnt(0)
	v_add_f32_e32 v128, v128, v129
	global_store_dword v[132:133], v128, off
;     __device__ __forceinline__ void operator()(const f32x4 (&acc)[2][2][4][2], const Unit& u, int wr, int wc, int fr, int fq) const {
;     ...
;             for (int m = 0; m < 4; ++m) { const int row = row0 + ai * HALF + m * 16; const size_t off = (size_t)row * DM + col0; float s = 0.f;
; #pragma unroll
;                 for (int bj = 0; bj < 2; ++bj)
; #pragma unroll
;                     for (int n = 0; n < 2; ++n) { const f32x4 xv = *(const f32x4*)(base + off + bj * HALF + n * 16); const f32x4 o = xv + gv[bj][n] * acc[ai][bj][m][n];
;                         *(f32x4*)(out + off + bj * HALF + n * 16) = o; s += (o[0] * o[0] + o[1] * o[1]) + (o[2] * o[2] + o[3] * o[3]); }
;                 s += __shfl_xor(s, 16); s += __shfl_xor(s, 32);
;                 if (fq == 0) ssq[(size_t)row * 16 + u.pn * 4 + wc] = s; }
.LBB0_1084:
	s_or_b64 exec, exec, s[24:25]
	v_or_b32_e32 v128, 16, v154
	s_waitcnt lgkmcnt(0)
	v_ashrrev_i32_e32 v129, 31, v128
	v_lshlrev_b64 v[132:133], 12, v[128:129]
	v_lshl_add_u64 v[132:133], s[30:31], 0, v[132:133]
	v_lshl_add_u64 v[176:177], v[152:153], 2, v[132:133]
	global_load_dwordx4 v[132:135], v[176:177], off
	global_load_dwordx4 v[136:139], v[176:177], off offset:64
	global_load_dwordx4 v[140:143], v[176:177], off offset:512
	global_load_dwordx4 v[172:175], v[176:177], off offset:576
	s_waitcnt vmcnt(3)
	v_pk_fma_f32 v[126:127], v[126:127], v[102:103], v[134:135]
	v_pk_fma_f32 v[124:125], v[124:125], v[100:101], v[132:133]
	s_waitcnt vmcnt(2)
	v_pk_fma_f32 v[122:123], v[122:123], v[98:99], v[138:139]
	v_pk_fma_f32 v[120:121], v[120:121], v[96:97], v[136:137]
	s_waitcnt vmcnt(1)
	v_pk_fma_f32 v[118:119], v[118:119], v[114:115], v[142:143]
	v_pk_fma_f32 v[116:117], v[116:117], v[112:113], v[140:141]
	s_waitcnt vmcnt(0)
	v_pk_fma_f32 v[134:135], v[110:111], v[106:107], v[174:175]
	v_pk_fma_f32 v[132:133], v[108:109], v[104:105], v[172:173]
	v_mul_f32_e32 v108, v125, v125
	v_mul_f32_e32 v109, v127, v127
	v_mul_f32_e32 v110, v121, v121
	v_mul_f32_e32 v111, v123, v123
	v_mul_f32_e32 v131, v117, v117
	v_mul_f32_e32 v136, v119, v119
	v_fmac_f32_e32 v108, v124, v124
	v_fmac_f32_e32 v109, v126, v126
	v_fmac_f32_e32 v110, v120, v120
	v_fmac_f32_e32 v111, v122, v122
	v_mul_f32_e32 v137, v133, v133
	v_mul_f32_e32 v138, v135, v135
	v_fmac_f32_e32 v131, v116, v116
	v_fmac_f32_e32 v136, v118, v118
	v_add_f32_e32 v108, v108, v109
	v_add_f32_e32 v109, v110, v111
	v_fmac_f32_e32 v137, v132, v132
	v_fmac_f32_e32 v138, v134, v134
	v_add_f32_e32 v110, v131, v136
	v_add_f32_e32 v108, v108, v109
	v_add_f32_e32 v108, v108, v110
	v_add_f32_e32 v109, v137, v138
	v_add_f32_e32 v108, v108, v109
	ds_bpermute_b32 v109, v169, v108
	global_store_dwordx4 v[176:177], v[124:127], off sc1
	global_store_dwordx4 v[176:177], v[120:123], off offset:64 sc1
	global_store_dwordx4 v[176:177], v[116:119], off offset:512 sc1
	global_store_dwordx4 v[176:177], v[132:135], off offset:576 sc1
	s_waitcnt lgkmcnt(0)
	v_add_f32_e32 v108, v108, v109
	ds_bpermute_b32 v109, v130, v108
	s_and_saveexec_b64 s[24:25], s[0:1]
	s_cbranch_execz .LBB0_1086
	v_lshlrev_b64 v[110:111], 6, v[128:129]
	v_lshl_add_u64 v[110:111], s[6:7], 0, v[110:111]
	v_lshl_add_u64 v[110:111], s[22:23], 2, v[110:111]
	s_lshl_b32 s8, s48, 2
	v_lshl_add_u64 v[110:111], v[110:111], 0, s[8:9]
	s_waitcnt lgkmcnt(0)
	v_add_f32_e32 v108, v108, v109
	global_store_dword v[110:111], v108, off
.LBB0_1086:
	s_or_b64 exec, exec, s[24:25]
	v_or_b32_e32 v108, 32, v154
	s_waitcnt lgkmcnt(0)
	v_ashrrev_i32_e32 v109, 31, v108
	v_lshlrev_b64 v[110:111], 12, v[108:109]
	v_lshl_add_u64 v[110:111], s[30:31], 0, v[110:111]
	v_lshl_add_u64 v[110:111], v[152:153], 2, v[110:111]
	global_load_dwordx4 v[116:119], v[110:111], off
	global_load_dwordx4 v[120:123], v[110:111], off offset:64
	global_load_dwordx4 v[124:127], v[110:111], off offset:512
	global_load_dwordx4 v[132:135], v[110:111], off offset:576
	s_waitcnt vmcnt(3)
	v_pk_fma_f32 v[94:95], v[94:95], v[102:103], v[118:119]
	v_pk_fma_f32 v[92:93], v[92:93], v[100:101], v[116:117]
	s_waitcnt vmcnt(2)
	v_pk_fma_f32 v[90:91], v[90:91], v[98:99], v[122:123]
	v_pk_fma_f32 v[88:89], v[88:89], v[96:97], v[120:121]
	s_waitcnt vmcnt(1)
	v_pk_fma_f32 v[86:87], v[86:87], v[114:115], v[126:127]
	v_pk_fma_f32 v[84:85], v[84:85], v[112:113], v[124:125]
	s_waitcnt vmcnt(0)
	v_pk_fma_f32 v[118:119], v[82:83], v[106:107], v[134:135]
	v_pk_fma_f32 v[116:117], v[80:81], v[104:105], v[132:133]
	v_mul_f32_e32 v80, v93, v93
	v_mul_f32_e32 v81, v95, v95
	v_mul_f32_e32 v82, v89, v89
	v_mul_f32_e32 v83, v91, v91
	v_mul_f32_e32 v120, v85, v85
	v_mul_f32_e32 v121, v87, v87
	v_fmac_f32_e32 v80, v92, v92
	v_fmac_f32_e32 v81, v94, v94
	v_fmac_f32_e32 v82, v88, v88
	v_fmac_f32_e32 v83, v90, v90
	v_mul_f32_e32 v122, v117, v117
	v_mul_f32_e32 v123, v119, v119
	v_fmac_f32_e32 v120, v84, v84
	v_fmac_f32_e32 v121, v86, v86
	v_add_f32_e32 v80, v80, v81
	v_add_f32_e32 v81, v82, v83
	v_fmac_f32_e32 v122, v116, v116
	v_fmac_f32_e32 v123, v118, v118
	v_add_f32_e32 v82, v120, v121
	v_add_f32_e32 v80, v80, v81
	v_add_f32_e32 v80, v80, v82
	v_add_f32_e32 v81, v122, v123
	v_add_f32_e32 v80, v80, v81
	ds_bpermute_b32 v81, v169, v80
	global_store_dwordx4 v[110:111], v[92:95], off sc1
	global_store_dwordx4 v[110:111], v[88:91], off offset:64 sc1
	global_store_dwordx4 v[110:111], v[84:87], off offset:512 sc1
	global_store_dwordx4 v[110:111], v[116:119], off offset:576 sc1
	s_waitcnt lgkmcnt(0)
	v_add_f32_e32 v80, v80, v81
	ds_bpermute_b32 v81, v130, v80
	s_and_saveexec_b64 s[24:25], s[0:1]
	s_cbranch_execz .LBB0_1088
	v_lshlrev_b64 v[82:83], 6, v[108:109]
	v_lshl_add_u64 v[82:83], s[6:7], 0, v[82:83]
	v_lshl_add_u64 v[82:83], s[22:23], 2, v[82:83]
	s_lshl_b32 s8, s48, 2
	v_lshl_add_u64 v[82:83], v[82:83], 0, s[8:9]
	s_waitcnt lgkmcnt(0)
	v_add_f32_e32 v80, v80, v81
	global_store_dword v[82:83], v80, off
;     __device__ __forceinline__ void operator()(const f32x4 (&acc)[2][2][4][2], const Unit& u, int wr, int wc, int fr, int fq) const {
;     ...
;             for (int m = 0; m < 4; ++m) { const int row = row0 + ai * HALF + m * 16; const size_t off = (size_t)row * DM + col0; float s = 0.f;
; #pragma unroll
;                 for (int bj = 0; bj < 2; ++bj)
; #pragma unroll
;                     for (int n = 0; n < 2; ++n) { const f32x4 xv = *(const f32x4*)(base + off + bj * HALF + n * 16); const f32x4 o = xv + gv[bj][n] * acc[ai][bj][m][n];
;                         *(f32x4*)(out + off + bj * HALF + n * 16) = o; s += (o[0] * o[0] + o[1] * o[1]) + (o[2] * o[2] + o[3] * o[3]); }
;                 s += __shfl_xor(s, 16); s += __shfl_xor(s, 32);
;                 if (fq == 0) ssq[(size_t)row * 16 + u.pn * 4 + wc] = s; }
.LBB0_1088:
	s_or_b64 exec, exec, s[24:25]
	v_or_b32_e32 v80, 48, v154
	s_waitcnt lgkmcnt(0)
	v_ashrrev_i32_e32 v81, 31, v80
	v_lshlrev_b64 v[82:83], 12, v[80:81]
	v_lshl_add_u64 v[82:83], s[30:31], 0, v[82:83]
	v_lshl_add_u64 v[94:95], v[152:153], 2, v[82:83]
	global_load_dwordx4 v[82:85], v[94:95], off
	global_load_dwordx4 v[86:89], v[94:95], off offset:64
	global_load_dwordx4 v[90:93], v[94:95], off offset:512
	global_load_dwordx4 v[108:111], v[94:95], off offset:576
	s_waitcnt vmcnt(3)
	v_pk_fma_f32 v[78:79], v[78:79], v[102:103], v[84:85]
	v_pk_fma_f32 v[76:77], v[76:77], v[100:101], v[82:83]
	s_waitcnt vmcnt(2)
	v_pk_fma_f32 v[74:75], v[74:75], v[98:99], v[88:89]
	v_pk_fma_f32 v[72:73], v[72:73], v[96:97], v[86:87]
	s_waitcnt vmcnt(1)
	v_pk_fma_f32 v[70:71], v[70:71], v[114:115], v[92:93]
	v_pk_fma_f32 v[68:69], v[68:69], v[112:113], v[90:91]
	s_waitcnt vmcnt(0)
	v_pk_fma_f32 v[84:85], v[66:67], v[106:107], v[110:111]
	v_pk_fma_f32 v[82:83], v[64:65], v[104:105], v[108:109]
	v_mul_f32_e32 v64, v77, v77
	v_mul_f32_e32 v65, v79, v79
	v_mul_f32_e32 v66, v73, v73
	v_mul_f32_e32 v67, v75, v75
	v_mul_f32_e32 v86, v69, v69
	v_mul_f32_e32 v87, v71, v71
	v_fmac_f32_e32 v64, v76, v76
	v_fmac_f32_e32 v65, v78, v78
	v_fmac_f32_e32 v66, v72, v72
	v_fmac_f32_e32 v67, v74, v74
	v_mul_f32_e32 v88, v83, v83
	v_mul_f32_e32 v89, v85, v85
	v_fmac_f32_e32 v86, v68, v68
	v_fmac_f32_e32 v87, v70, v70
	v_add_f32_e32 v64, v64, v65
	v_add_f32_e32 v65, v66, v67
	v_fmac_f32_e32 v88, v82, v82
	v_fmac_f32_e32 v89, v84, v84
	v_add_f32_e32 v66, v86, v87
	v_add_f32_e32 v64, v64, v65
	v_add_f32_e32 v64, v64, v66
	v_add_f32_e32 v65, v88, v89
	v_add_f32_e32 v64, v64, v65
	ds_bpermute_b32 v65, v169, v64
	global_store_dwordx4 v[94:95], v[76:79], off sc1
	global_store_dwordx4 v[94:95], v[72:75], off offset:64 sc1
	global_store_dwordx4 v[94:95], v[68:71], off offset:512 sc1
	global_store_dwordx4 v[94:95], v[82:85], off offset:576 sc1
	s_waitcnt lgkmcnt(0)
	v_add_f32_e32 v64, v64, v65
	ds_bpermute_b32 v65, v130, v64
	s_and_saveexec_b64 s[24:25], s[0:1]
	s_cbranch_execz .LBB0_1090
	v_lshlrev_b64 v[66:67], 6, v[80:81]
	v_lshl_add_u64 v[66:67], s[6:7], 0, v[66:67]
	v_lshl_add_u64 v[66:67], s[22:23], 2, v[66:67]
	s_lshl_b32 s8, s48, 2
	v_lshl_add_u64 v[66:67], v[66:67], 0, s[8:9]
	s_waitcnt lgkmcnt(0)
	v_add_f32_e32 v64, v64, v65
	global_store_dword v[66:67], v64, off
.LBB0_1090:
	s_or_b64 exec, exec, s[24:25]
	v_add_u32_e32 v64, 0x80, v154
	s_waitcnt lgkmcnt(0)
	v_ashrrev_i32_e32 v65, 31, v64
	v_lshlrev_b64 v[66:67], 12, v[64:65]
	v_lshl_add_u64 v[66:67], s[30:31], 0, v[66:67]
	v_lshl_add_u64 v[82:83], v[152:153], 2, v[66:67]
	global_load_dwordx4 v[66:69], v[82:83], off
	global_load_dwordx4 v[70:73], v[82:83], off offset:64
	global_load_dwordx4 v[74:77], v[82:83], off offset:512
	global_load_dwordx4 v[78:81], v[82:83], off offset:576
	s_waitcnt vmcnt(3)
	v_pk_fma_f32 v[62:63], v[62:63], v[102:103], v[68:69]
	v_pk_fma_f32 v[60:61], v[60:61], v[100:101], v[66:67]
	s_waitcnt vmcnt(2)
	v_pk_fma_f32 v[58:59], v[58:59], v[98:99], v[72:73]
	v_pk_fma_f32 v[56:57], v[56:57], v[96:97], v[70:71]
	s_waitcnt vmcnt(1)
	v_pk_fma_f32 v[54:55], v[54:55], v[114:115], v[76:77]
	v_pk_fma_f32 v[52:53], v[52:53], v[112:113], v[74:75]
	s_waitcnt vmcnt(0)
	v_pk_fma_f32 v[68:69], v[50:51], v[106:107], v[80:81]
	v_pk_fma_f32 v[66:67], v[48:49], v[104:105], v[78:79]
	v_mul_f32_e32 v48, v61, v61
	v_mul_f32_e32 v49, v63, v63
	v_mul_f32_e32 v50, v57, v57
	v_mul_f32_e32 v51, v59, v59
	v_mul_f32_e32 v70, v53, v53
	v_mul_f32_e32 v71, v55, v55
	v_fmac_f32_e32 v48, v60, v60
	v_fmac_f32_e32 v49, v62, v62
	v_fmac_f32_e32 v50, v56, v56
	v_fmac_f32_e32 v51, v58, v58
	v_mul_f32_e32 v72, v67, v67
	v_mul_f32_e32 v73, v69, v69
	v_fmac_f32_e32 v70, v52, v52
	v_fmac_f32_e32 v71, v54, v54
	v_add_f32_e32 v48, v48, v49
	v_add_f32_e32 v49, v50, v51
	v_fmac_f32_e32 v72, v66, v66
	v_fmac_f32_e32 v73, v68, v68
	v_add_f32_e32 v50, v70, v71
	v_add_f32_e32 v48, v48, v49
	v_add_f32_e32 v48, v48, v50
	v_add_f32_e32 v49, v72, v73
	v_add_f32_e32 v48, v48, v49
	ds_bpermute_b32 v49, v169, v48
	global_store_dwordx4 v[82:83], v[60:63], off sc1
	global_store_dwordx4 v[82:83], v[56:59], off offset:64 sc1
	global_store_dwordx4 v[82:83], v[52:55], off offset:512 sc1
	global_store_dwordx4 v[82:83], v[66:69], off offset:576 sc1
	s_waitcnt lgkmcnt(0)
	v_add_f32_e32 v48, v48, v49
	ds_bpermute_b32 v49, v130, v48
	s_and_saveexec_b64 s[24:25], s[0:1]
	s_cbranch_execz .LBB0_1092
	v_lshlrev_b64 v[50:51], 6, v[64:65]
	v_lshl_add_u64 v[50:51], s[6:7], 0, v[50:51]
	v_lshl_add_u64 v[50:51], s[22:23], 2, v[50:51]
	s_lshl_b32 s8, s48, 2
	v_lshl_add_u64 v[50:51], v[50:51], 0, s[8:9]
	s_waitcnt lgkmcnt(0)
	v_add_f32_e32 v48, v48, v49
	global_store_dword v[50:51], v48, off
;     __device__ __forceinline__ void operator()(const f32x4 (&acc)[2][2][4][2], const Unit& u, int wr, int wc, int fr, int fq) const {
;     ...
;             for (int m = 0; m < 4; ++m) { const int row = row0 + ai * HALF + m * 16; const size_t off = (size_t)row * DM + col0; float s = 0.f;
; #pragma unroll
;                 for (int bj = 0; bj < 2; ++bj)
; #pragma unroll
;                     for (int n = 0; n < 2; ++n) { const f32x4 xv = *(const f32x4*)(base + off + bj * HALF + n * 16); const f32x4 o = xv + gv[bj][n] * acc[ai][bj][m][n];
;                         *(f32x4*)(out + off + bj * HALF + n * 16) = o; s += (o[0] * o[0] + o[1] * o[1]) + (o[2] * o[2] + o[3] * o[3]); }
;                 s += __shfl_xor(s, 16); s += __shfl_xor(s, 32);
;                 if (fq == 0) ssq[(size_t)row * 16 + u.pn * 4 + wc] = s; }
.LBB0_1092:
	s_or_b64 exec, exec, s[24:25]
	v_add_u32_e32 v48, 0x90, v154
	s_waitcnt lgkmcnt(0)
	v_ashrrev_i32_e32 v49, 31, v48
	v_lshlrev_b64 v[50:51], 12, v[48:49]
	v_lshl_add_u64 v[50:51], s[30:31], 0, v[50:51]
	v_lshl_add_u64 v[66:67], v[152:153], 2, v[50:51]
	global_load_dwordx4 v[50:53], v[66:67], off
	global_load_dwordx4 v[54:57], v[66:67], off offset:64
	global_load_dwordx4 v[58:61], v[66:67], off offset:512
	global_load_dwordx4 v[62:65], v[66:67], off offset:576
	s_waitcnt vmcnt(3)
	v_pk_fma_f32 v[46:47], v[46:47], v[102:103], v[52:53]
	v_pk_fma_f32 v[44:45], v[44:45], v[100:101], v[50:51]
	s_waitcnt vmcnt(2)
	v_pk_fma_f32 v[42:43], v[42:43], v[98:99], v[56:57]
	v_pk_fma_f32 v[40:41], v[40:41], v[96:97], v[54:55]
	s_waitcnt vmcnt(1)
	v_pk_fma_f32 v[38:39], v[38:39], v[114:115], v[60:61]
	v_pk_fma_f32 v[36:37], v[36:37], v[112:113], v[58:59]
	s_waitcnt vmcnt(0)
	v_pk_fma_f32 v[52:53], v[34:35], v[106:107], v[64:65]
	v_pk_fma_f32 v[50:51], v[32:33], v[104:105], v[62:63]
	v_mul_f32_e32 v32, v45, v45
	v_mul_f32_e32 v33, v47, v47
	v_mul_f32_e32 v34, v41, v41
	v_mul_f32_e32 v35, v43, v43
	v_mul_f32_e32 v54, v37, v37
	v_mul_f32_e32 v55, v39, v39
	v_fmac_f32_e32 v32, v44, v44
	v_fmac_f32_e32 v33, v46, v46
	v_fmac_f32_e32 v34, v40, v40
	v_fmac_f32_e32 v35, v42, v42
	v_mul_f32_e32 v56, v51, v51
	v_mul_f32_e32 v57, v53, v53
	v_fmac_f32_e32 v54, v36, v36
	v_fmac_f32_e32 v55, v38, v38
	v_add_f32_e32 v32, v32, v33
	v_add_f32_e32 v33, v34, v35
	v_fmac_f32_e32 v56, v50, v50
	v_fmac_f32_e32 v57, v52, v52
	v_add_f32_e32 v34, v54, v55
	v_add_f32_e32 v32, v32, v33
	v_add_f32_e32 v32, v32, v34
	v_add_f32_e32 v33, v56, v57
	v_add_f32_e32 v32, v32, v33
	ds_bpermute_b32 v33, v169, v32
	global_store_dwordx4 v[66:67], v[44:47], off sc1
	global_store_dwordx4 v[66:67], v[40:43], off offset:64 sc1
	global_store_dwordx4 v[66:67], v[36:39], off offset:512 sc1
	global_store_dwordx4 v[66:67], v[50:53], off offset:576 sc1
	s_waitcnt lgkmcnt(0)
	v_add_f32_e32 v32, v32, v33
	ds_bpermute_b32 v33, v130, v32
	s_and_saveexec_b64 s[24:25], s[0:1]
	s_cbranch_execz .LBB0_1094
	v_lshlrev_b64 v[34:35], 6, v[48:49]
	v_lshl_add_u64 v[34:35], s[6:7], 0, v[34:35]
	v_lshl_add_u64 v[34:35], s[22:23], 2, v[34:35]
	s_lshl_b32 s8, s48, 2
	v_lshl_add_u64 v[34:35], v[34:35], 0, s[8:9]
	s_waitcnt lgkmcnt(0)
	v_add_f32_e32 v32, v32, v33
	global_store_dword v[34:35], v32, off
.LBB0_1094:
	s_or_b64 exec, exec, s[24:25]
	v_add_u32_e32 v32, 0xa0, v154
	s_waitcnt lgkmcnt(0)
	v_ashrrev_i32_e32 v33, 31, v32
	v_lshlrev_b64 v[34:35], 12, v[32:33]
	v_lshl_add_u64 v[34:35], s[30:31], 0, v[34:35]
	v_lshl_add_u64 v[50:51], v[152:153], 2, v[34:35]
	global_load_dwordx4 v[34:37], v[50:51], off
	global_load_dwordx4 v[38:41], v[50:51], off offset:64
	global_load_dwordx4 v[42:45], v[50:51], off offset:512
	global_load_dwordx4 v[46:49], v[50:51], off offset:576
	s_waitcnt vmcnt(3)
	v_pk_fma_f32 v[30:31], v[30:31], v[102:103], v[36:37]
	v_pk_fma_f32 v[28:29], v[28:29], v[100:101], v[34:35]
	s_waitcnt vmcnt(2)
	v_pk_fma_f32 v[26:27], v[26:27], v[98:99], v[40:41]
	v_pk_fma_f32 v[24:25], v[24:25], v[96:97], v[38:39]
	s_waitcnt vmcnt(1)
	v_pk_fma_f32 v[22:23], v[22:23], v[114:115], v[44:45]
	v_pk_fma_f32 v[20:21], v[20:21], v[112:113], v[42:43]
	s_waitcnt vmcnt(0)
	v_pk_fma_f32 v[36:37], v[18:19], v[106:107], v[48:49]
	v_pk_fma_f32 v[34:35], v[16:17], v[104:105], v[46:47]
	v_mul_f32_e32 v16, v29, v29
	v_mul_f32_e32 v17, v31, v31
	v_mul_f32_e32 v18, v25, v25
	v_mul_f32_e32 v19, v27, v27
	v_mul_f32_e32 v38, v21, v21
	v_mul_f32_e32 v39, v23, v23
	v_fmac_f32_e32 v16, v28, v28
	v_fmac_f32_e32 v17, v30, v30
	v_fmac_f32_e32 v18, v24, v24
	v_fmac_f32_e32 v19, v26, v26
	v_mul_f32_e32 v40, v35, v35
	v_mul_f32_e32 v41, v37, v37
	v_fmac_f32_e32 v38, v20, v20
	v_fmac_f32_e32 v39, v22, v22
	v_add_f32_e32 v16, v16, v17
	v_add_f32_e32 v17, v18, v19
	v_fmac_f32_e32 v40, v34, v34
	v_fmac_f32_e32 v41, v36, v36
	v_add_f32_e32 v18, v38, v39
	v_add_f32_e32 v16, v16, v17
	v_add_f32_e32 v16, v16, v18
	v_add_f32_e32 v17, v40, v41
	v_add_f32_e32 v16, v16, v17
	ds_bpermute_b32 v17, v169, v16
	global_store_dwordx4 v[50:51], v[28:31], off sc1
	global_store_dwordx4 v[50:51], v[24:27], off offset:64 sc1
	global_store_dwordx4 v[50:51], v[20:23], off offset:512 sc1
	global_store_dwordx4 v[50:51], v[34:37], off offset:576 sc1
	s_waitcnt lgkmcnt(0)
	v_add_f32_e32 v16, v16, v17
	ds_bpermute_b32 v17, v130, v16
	s_and_saveexec_b64 s[24:25], s[0:1]
	s_cbranch_execz .LBB0_1096
	v_lshlrev_b64 v[18:19], 6, v[32:33]
	v_lshl_add_u64 v[18:19], s[6:7], 0, v[18:19]
	v_lshl_add_u64 v[18:19], s[22:23], 2, v[18:19]
	s_lshl_b32 s8, s48, 2
	v_lshl_add_u64 v[18:19], v[18:19], 0, s[8:9]
	s_waitcnt lgkmcnt(0)
	v_add_f32_e32 v16, v16, v17
	global_store_dword v[18:19], v16, off
.LBB0_1096:
	s_or_b64 exec, exec, s[24:25]
	v_add_u32_e32 v16, 0xb0, v154
	s_waitcnt lgkmcnt(0)
	v_ashrrev_i32_e32 v17, 31, v16
	v_lshlrev_b64 v[18:19], 12, v[16:17]
	v_lshl_add_u64 v[18:19], s[30:31], 0, v[18:19]
	v_lshl_add_u64 v[34:35], v[152:153], 2, v[18:19]
	global_load_dwordx4 v[18:21], v[34:35], off
	global_load_dwordx4 v[22:25], v[34:35], off offset:64
	global_load_dwordx4 v[26:29], v[34:35], off offset:512
	global_load_dwordx4 v[30:33], v[34:35], off offset:576
	s_waitcnt vmcnt(3)
	v_pk_fma_f32 v[14:15], v[14:15], v[102:103], v[20:21]
	v_pk_fma_f32 v[12:13], v[12:13], v[100:101], v[18:19]
	s_waitcnt vmcnt(2)
	v_pk_fma_f32 v[10:11], v[10:11], v[98:99], v[24:25]
	v_pk_fma_f32 v[8:9], v[8:9], v[96:97], v[22:23]
	s_waitcnt vmcnt(1)
	v_pk_fma_f32 v[6:7], v[6:7], v[114:115], v[28:29]
	v_pk_fma_f32 v[4:5], v[4:5], v[112:113], v[26:27]
	s_waitcnt vmcnt(0)
	v_pk_fma_f32 v[20:21], v[2:3], v[106:107], v[32:33]
	v_pk_fma_f32 v[18:19], v[0:1], v[104:105], v[30:31]
	v_mul_f32_e32 v0, v13, v13
	v_mul_f32_e32 v1, v15, v15
	v_mul_f32_e32 v2, v9, v9
	v_mul_f32_e32 v3, v11, v11
	v_mul_f32_e32 v22, v5, v5
	v_mul_f32_e32 v23, v7, v7
	v_fmac_f32_e32 v0, v12, v12
	v_fmac_f32_e32 v1, v14, v14
	v_fmac_f32_e32 v2, v8, v8
	v_fmac_f32_e32 v3, v10, v10
	v_mul_f32_e32 v24, v19, v19
	v_mul_f32_e32 v25, v21, v21
	v_fmac_f32_e32 v22, v4, v4
	v_fmac_f32_e32 v23, v6, v6
	v_add_f32_e32 v0, v0, v1
	v_add_f32_e32 v1, v2, v3
	v_fmac_f32_e32 v24, v18, v18
	v_fmac_f32_e32 v25, v20, v20
	v_add_f32_e32 v2, v22, v23
	v_add_f32_e32 v0, v0, v1
	v_add_f32_e32 v0, v0, v2
	v_add_f32_e32 v1, v24, v25
	v_add_f32_e32 v0, v0, v1
	ds_bpermute_b32 v1, v169, v0
	global_store_dwordx4 v[34:35], v[12:15], off sc1
	global_store_dwordx4 v[34:35], v[8:11], off offset:64 sc1
	global_store_dwordx4 v[34:35], v[4:7], off offset:512 sc1
	global_store_dwordx4 v[34:35], v[18:21], off offset:576 sc1
	s_waitcnt lgkmcnt(0)
	v_add_f32_e32 v0, v0, v1
	ds_bpermute_b32 v1, v130, v0
	s_and_saveexec_b64 s[24:25], s[0:1]
	s_cbranch_execz .LBB0_1073
	v_lshlrev_b64 v[2:3], 6, v[16:17]
	v_lshl_add_u64 v[2:3], s[6:7], 0, v[2:3]
	v_lshl_add_u64 v[2:3], s[22:23], 2, v[2:3]
	s_lshl_b32 s8, s48, 2
	v_lshl_add_u64 v[2:3], v[2:3], 0, s[8:9]
	s_waitcnt lgkmcnt(0)
	v_add_f32_e32 v0, v0, v1
	global_store_dword v[2:3], v0, off
	s_branch .LBB0_1073

; #define LAS __attribute__((address_space(3)))
;     __device__ __forceinline__ void fused(f32x4 (&acc)[2][2][4][2], const Unit& u, int wr, int wc, int fr, int fq, LAS unsigned char* lds, int wid, int lane) const {
;     ...
;         const LAS float* S = (const LAS float*)(lds + 4096);
;         f32x4 gg[2][2];
; #pragma unroll
;         for (int bj = 0; bj < 2; ++bj)
; #pragma unroll
;             for (int n = 0; n < 2; ++n) gg[bj][n] = *(const f32x4*)(g + col0 + bj * HALF + n * 16);
; #pragma unroll
;         for (int ai = 0; ai < 2; ++ai)
; #pragma unroll
;             for (int m = 0; m < 4; ++m) { const int r = ai * HALF + wr * 64 + m * 16 + fr; const float rstd = S[r]; float* rowp = out + (size_t)(u.pm * BM + r) * DM + col0;
; #pragma unroll
;                 for (int bj = 0; bj < 2; ++bj)
; #pragma unroll
;                     for (int n = 0; n < 2; ++n) *(f32x4*)(rowp + bj * HALF + n * 16) = (acc[ai][bj][m][n] * rstd) * gg[bj][n];
;                 asm volatile("" ::: "memory"); }
.LBB0_1158:
	s_or_b64 exec, exec, s[8:9]
	v_lshlrev_b64 v[144:145], 2, v[144:145]
	s_waitcnt lgkmcnt(0)
	s_barrier
	v_lshl_add_u64 v[128:129], s[28:29], 0, v[144:145]
	global_load_dwordx4 v[140:143], v[128:129], off
	global_load_dwordx4 v[136:139], v[128:129], off offset:64
	global_load_dwordx4 v[132:135], v[128:129], off offset:512
	s_nop 0
	global_load_dwordx4 v[128:131], v[128:129], off offset:576
	v_lshl_add_u32 v164, v152, 2, 0
	ds_read_b32 v148, v164 offset:4096
	v_add_u32_e32 v146, s10, v152
	v_ashrrev_i32_e32 v147, 31, v146
	v_lshlrev_b64 v[156:157], 12, v[146:147]
	v_lshl_add_u64 v[156:157], s[30:31], 0, v[156:157]
	s_waitcnt lgkmcnt(0)
	v_pk_mul_f32 v[120:121], v[120:121], v[148:149] op_sel_hi:[1,0]
	v_pk_mul_f32 v[122:123], v[122:123], v[148:149] op_sel_hi:[1,0]
	v_lshl_add_u64 v[156:157], v[156:157], 0, v[144:145]
	v_pk_mul_f32 v[124:125], v[124:125], v[148:149] op_sel_hi:[1,0]
	v_pk_mul_f32 v[126:127], v[126:127], v[148:149] op_sel_hi:[1,0]
	v_pk_mul_f32 v[158:159], v[116:117], v[148:149] op_sel_hi:[1,0]
	v_pk_mul_f32 v[160:161], v[118:119], v[148:149] op_sel_hi:[1,0]
	v_pk_mul_f32 v[162:163], v[112:113], v[148:149] op_sel_hi:[1,0]
	v_pk_mul_f32 v[148:149], v[114:115], v[148:149] op_sel_hi:[1,0]
	v_add_u32_e32 v150, 16, v146
	v_ashrrev_i32_e32 v151, 31, v150
	v_add_u32_e32 v152, 32, v146
	v_ashrrev_i32_e32 v153, 31, v152
	v_add_u32_e32 v154, 48, v146
	v_ashrrev_i32_e32 v155, 31, v154
	s_waitcnt vmcnt(3)
	v_pk_mul_f32 v[114:115], v[142:143], v[122:123]
	v_pk_mul_f32 v[112:113], v[140:141], v[120:121]
	s_waitcnt vmcnt(2)
	v_pk_mul_f32 v[118:119], v[138:139], v[126:127]
	v_pk_mul_f32 v[116:117], v[136:137], v[124:125]
	s_waitcnt vmcnt(1)
	v_pk_mul_f32 v[122:123], v[134:135], v[160:161]
	v_pk_mul_f32 v[120:121], v[132:133], v[158:159]
	s_waitcnt vmcnt(0)
	v_pk_mul_f32 v[126:127], v[130:131], v[148:149]
	v_pk_mul_f32 v[124:125], v[128:129], v[162:163]
	global_store_dwordx4 v[156:157], v[112:115], off sc1
	global_store_dwordx4 v[156:157], v[116:119], off offset:64 sc1
	global_store_dwordx4 v[156:157], v[120:123], off offset:512 sc1
	global_store_dwordx4 v[156:157], v[124:127], off offset:576 sc1
	ds_read_b32 v112, v164 offset:4160
	v_lshlrev_b64 v[114:115], 12, v[150:151]
	v_lshl_add_u64 v[114:115], s[30:31], 0, v[114:115]
	v_lshl_add_u64 v[114:115], v[114:115], 0, v[144:145]
	s_waitcnt lgkmcnt(0)
	v_pk_mul_f32 v[108:109], v[108:109], v[112:113] op_sel_hi:[1,0]
	v_pk_mul_f32 v[110:111], v[110:111], v[112:113] op_sel_hi:[1,0]
	v_pk_mul_f32 v[104:105], v[104:105], v[112:113] op_sel_hi:[1,0]
	v_pk_mul_f32 v[106:107], v[106:107], v[112:113] op_sel_hi:[1,0]
	v_pk_mul_f32 v[116:117], v[100:101], v[112:113] op_sel_hi:[1,0]
	v_pk_mul_f32 v[118:119], v[102:103], v[112:113] op_sel_hi:[1,0]
	v_pk_mul_f32 v[120:121], v[96:97], v[112:113] op_sel_hi:[1,0]
	v_pk_mul_f32 v[112:113], v[98:99], v[112:113] op_sel_hi:[1,0]
	v_pk_mul_f32 v[98:99], v[142:143], v[110:111]
	v_pk_mul_f32 v[96:97], v[140:141], v[108:109]
	v_pk_mul_f32 v[102:103], v[138:139], v[106:107]
	v_pk_mul_f32 v[100:101], v[136:137], v[104:105]
	v_pk_mul_f32 v[106:107], v[134:135], v[118:119]
	v_pk_mul_f32 v[104:105], v[132:133], v[116:117]
	v_pk_mul_f32 v[110:111], v[130:131], v[112:113]
	v_pk_mul_f32 v[108:109], v[128:129], v[120:121]
	global_store_dwordx4 v[114:115], v[96:99], off sc1
	global_store_dwordx4 v[114:115], v[100:103], off offset:64 sc1
	global_store_dwordx4 v[114:115], v[104:107], off offset:512 sc1
	global_store_dwordx4 v[114:115], v[108:111], off offset:576 sc1
	ds_read_b32 v96, v164 offset:4224
	v_lshlrev_b64 v[98:99], 12, v[152:153]
	v_lshl_add_u64 v[98:99], s[30:31], 0, v[98:99]
	v_lshl_add_u64 v[98:99], v[98:99], 0, v[144:145]
	s_waitcnt lgkmcnt(0)
	v_pk_mul_f32 v[92:93], v[92:93], v[96:97] op_sel_hi:[1,0]
	v_pk_mul_f32 v[94:95], v[94:95], v[96:97] op_sel_hi:[1,0]
	v_pk_mul_f32 v[88:89], v[88:89], v[96:97] op_sel_hi:[1,0]
	v_pk_mul_f32 v[90:91], v[90:91], v[96:97] op_sel_hi:[1,0]
	v_pk_mul_f32 v[100:101], v[84:85], v[96:97] op_sel_hi:[1,0]
	v_pk_mul_f32 v[102:103], v[86:87], v[96:97] op_sel_hi:[1,0]
	v_pk_mul_f32 v[104:105], v[80:81], v[96:97] op_sel_hi:[1,0]
	v_pk_mul_f32 v[96:97], v[82:83], v[96:97] op_sel_hi:[1,0]
	v_pk_mul_f32 v[82:83], v[142:143], v[94:95]
	v_pk_mul_f32 v[80:81], v[140:141], v[92:93]
	v_pk_mul_f32 v[86:87], v[138:139], v[90:91]
	v_pk_mul_f32 v[84:85], v[136:137], v[88:89]
	v_pk_mul_f32 v[90:91], v[134:135], v[102:103]
	v_pk_mul_f32 v[88:89], v[132:133], v[100:101]
	v_pk_mul_f32 v[94:95], v[130:131], v[96:97]
	v_pk_mul_f32 v[92:93], v[128:129], v[104:105]
	global_store_dwordx4 v[98:99], v[80:83], off sc1
	global_store_dwordx4 v[98:99], v[84:87], off offset:64 sc1
	global_store_dwordx4 v[98:99], v[88:91], off offset:512 sc1
	global_store_dwordx4 v[98:99], v[92:95], off offset:576 sc1
	ds_read_b32 v80, v164 offset:4288
	v_lshlrev_b64 v[82:83], 12, v[154:155]
	v_lshl_add_u64 v[82:83], s[30:31], 0, v[82:83]
	v_lshl_add_u64 v[82:83], v[82:83], 0, v[144:145]
	s_waitcnt lgkmcnt(0)
	v_pk_mul_f32 v[76:77], v[76:77], v[80:81] op_sel_hi:[1,0]
	v_pk_mul_f32 v[78:79], v[78:79], v[80:81] op_sel_hi:[1,0]
	v_pk_mul_f32 v[64:65], v[64:65], v[80:81] op_sel_hi:[1,0]
	v_pk_mul_f32 v[66:67], v[66:67], v[80:81] op_sel_hi:[1,0]
	v_pk_mul_f32 v[72:73], v[72:73], v[80:81] op_sel_hi:[1,0]
	v_pk_mul_f32 v[74:75], v[74:75], v[80:81] op_sel_hi:[1,0]
	v_pk_mul_f32 v[84:85], v[68:69], v[80:81] op_sel_hi:[1,0]
	v_pk_mul_f32 v[86:87], v[70:71], v[80:81] op_sel_hi:[1,0]
	v_pk_mul_f32 v[70:71], v[142:143], v[78:79]
	v_pk_mul_f32 v[68:69], v[140:141], v[76:77]
	v_pk_mul_f32 v[66:67], v[130:131], v[66:67]
	v_pk_mul_f32 v[64:65], v[128:129], v[64:65]
	v_pk_mul_f32 v[74:75], v[138:139], v[74:75]
	v_pk_mul_f32 v[72:73], v[136:137], v[72:73]
	v_pk_mul_f32 v[78:79], v[134:135], v[86:87]
	v_pk_mul_f32 v[76:77], v[132:133], v[84:85]
	global_store_dwordx4 v[82:83], v[68:71], off sc1
	global_store_dwordx4 v[82:83], v[72:75], off offset:64 sc1
	global_store_dwordx4 v[82:83], v[76:79], off offset:512 sc1
	global_store_dwordx4 v[82:83], v[64:67], off offset:576 sc1
	ds_read_b32 v64, v164 offset:4608
	s_waitcnt lgkmcnt(0)
;     __device__ __forceinline__ void fused(f32x4 (&acc)[2][2][4][2], const Unit& u, int wr, int wc, int fr, int fq, LAS unsigned char* lds, int wid, int lane) const {
;     ...
;         for (int ai = 0; ai < 2; ++ai)
; #pragma unroll
;             for (int m = 0; m < 4; ++m) { const int r = ai * HALF + wr * 64 + m * 16 + fr; const float rstd = S[r]; float* rowp = out + (size_t)(u.pm * BM + r) * DM + col0;
; #pragma unroll
;                 for (int bj = 0; bj < 2; ++bj)
; #pragma unroll
;                     for (int n = 0; n < 2; ++n) *(f32x4*)(rowp + bj * HALF + n * 16) = (acc[ai][bj][m][n] * rstd) * gg[bj][n];
;                 asm volatile("" ::: "memory"); }
	v_pk_mul_f32 v[60:61], v[60:61], v[64:65] op_sel_hi:[1,0]
	v_add_u32_e32 v66, 0x80, v146
	v_ashrrev_i32_e32 v67, 31, v66
	v_lshlrev_b64 v[66:67], 12, v[66:67]
	v_lshl_add_u64 v[66:67], s[30:31], 0, v[66:67]
	v_pk_mul_f32 v[62:63], v[62:63], v[64:65] op_sel_hi:[1,0]
	v_pk_mul_f32 v[56:57], v[56:57], v[64:65] op_sel_hi:[1,0]
	v_pk_mul_f32 v[58:59], v[58:59], v[64:65] op_sel_hi:[1,0]
	v_pk_mul_f32 v[52:53], v[52:53], v[64:65] op_sel_hi:[1,0]
	v_pk_mul_f32 v[54:55], v[54:55], v[64:65] op_sel_hi:[1,0]
	v_pk_mul_f32 v[48:49], v[48:49], v[64:65] op_sel_hi:[1,0]
	v_pk_mul_f32 v[50:51], v[50:51], v[64:65] op_sel_hi:[1,0]
	v_lshl_add_u64 v[66:67], v[66:67], 0, v[144:145]
	v_pk_mul_f32 v[62:63], v[142:143], v[62:63]
	v_pk_mul_f32 v[60:61], v[140:141], v[60:61]
	v_pk_mul_f32 v[58:59], v[138:139], v[58:59]
	v_pk_mul_f32 v[56:57], v[136:137], v[56:57]
	v_pk_mul_f32 v[54:55], v[134:135], v[54:55]
	v_pk_mul_f32 v[52:53], v[132:133], v[52:53]
	v_pk_mul_f32 v[50:51], v[130:131], v[50:51]
	v_pk_mul_f32 v[48:49], v[128:129], v[48:49]
	global_store_dwordx4 v[66:67], v[60:63], off sc1
	global_store_dwordx4 v[66:67], v[56:59], off offset:64 sc1
	global_store_dwordx4 v[66:67], v[52:55], off offset:512 sc1
	global_store_dwordx4 v[66:67], v[48:51], off offset:576 sc1
	ds_read_b32 v48, v164 offset:4672
	s_waitcnt lgkmcnt(0)
	v_pk_mul_f32 v[44:45], v[44:45], v[48:49] op_sel_hi:[1,0]
	v_add_u32_e32 v50, 0x90, v146
	v_ashrrev_i32_e32 v51, 31, v50
	v_lshlrev_b64 v[50:51], 12, v[50:51]
	v_lshl_add_u64 v[50:51], s[30:31], 0, v[50:51]
	v_pk_mul_f32 v[46:47], v[46:47], v[48:49] op_sel_hi:[1,0]
	v_pk_mul_f32 v[40:41], v[40:41], v[48:49] op_sel_hi:[1,0]
	v_pk_mul_f32 v[42:43], v[42:43], v[48:49] op_sel_hi:[1,0]
	v_pk_mul_f32 v[36:37], v[36:37], v[48:49] op_sel_hi:[1,0]
	v_pk_mul_f32 v[38:39], v[38:39], v[48:49] op_sel_hi:[1,0]
	v_pk_mul_f32 v[32:33], v[32:33], v[48:49] op_sel_hi:[1,0]
	v_pk_mul_f32 v[34:35], v[34:35], v[48:49] op_sel_hi:[1,0]
	v_lshl_add_u64 v[50:51], v[50:51], 0, v[144:145]
	v_pk_mul_f32 v[46:47], v[142:143], v[46:47]
	v_pk_mul_f32 v[44:45], v[140:141], v[44:45]
	v_pk_mul_f32 v[42:43], v[138:139], v[42:43]
	v_pk_mul_f32 v[40:41], v[136:137], v[40:41]
	v_pk_mul_f32 v[38:39], v[134:135], v[38:39]
	v_pk_mul_f32 v[36:37], v[132:133], v[36:37]
	v_pk_mul_f32 v[34:35], v[130:131], v[34:35]
	v_pk_mul_f32 v[32:33], v[128:129], v[32:33]
	global_store_dwordx4 v[50:51], v[44:47], off sc1
	global_store_dwordx4 v[50:51], v[40:43], off offset:64 sc1
	global_store_dwordx4 v[50:51], v[36:39], off offset:512 sc1
	global_store_dwordx4 v[50:51], v[32:35], off offset:576 sc1
	ds_read_b32 v32, v164 offset:4736
	s_waitcnt lgkmcnt(0)
	v_pk_mul_f32 v[28:29], v[28:29], v[32:33] op_sel_hi:[1,0]
	v_add_u32_e32 v34, 0xa0, v146
	v_ashrrev_i32_e32 v35, 31, v34
	v_lshlrev_b64 v[34:35], 12, v[34:35]
	v_lshl_add_u64 v[34:35], s[30:31], 0, v[34:35]
	v_pk_mul_f32 v[30:31], v[30:31], v[32:33] op_sel_hi:[1,0]
	v_pk_mul_f32 v[24:25], v[24:25], v[32:33] op_sel_hi:[1,0]
	v_pk_mul_f32 v[26:27], v[26:27], v[32:33] op_sel_hi:[1,0]
	v_pk_mul_f32 v[20:21], v[20:21], v[32:33] op_sel_hi:[1,0]
	v_pk_mul_f32 v[22:23], v[22:23], v[32:33] op_sel_hi:[1,0]
	v_pk_mul_f32 v[16:17], v[16:17], v[32:33] op_sel_hi:[1,0]
	v_pk_mul_f32 v[18:19], v[18:19], v[32:33] op_sel_hi:[1,0]
	v_lshl_add_u64 v[34:35], v[34:35], 0, v[144:145]
	v_pk_mul_f32 v[30:31], v[142:143], v[30:31]
	v_pk_mul_f32 v[28:29], v[140:141], v[28:29]
	v_pk_mul_f32 v[26:27], v[138:139], v[26:27]
	v_pk_mul_f32 v[24:25], v[136:137], v[24:25]
	v_pk_mul_f32 v[22:23], v[134:135], v[22:23]
	v_pk_mul_f32 v[20:21], v[132:133], v[20:21]
	v_pk_mul_f32 v[18:19], v[130:131], v[18:19]
	v_pk_mul_f32 v[16:17], v[128:129], v[16:17]
	global_store_dwordx4 v[34:35], v[28:31], off sc1
	global_store_dwordx4 v[34:35], v[24:27], off offset:64 sc1
	global_store_dwordx4 v[34:35], v[20:23], off offset:512 sc1
	global_store_dwordx4 v[34:35], v[16:19], off offset:576 sc1
	ds_read_b32 v16, v164 offset:4800
	s_waitcnt lgkmcnt(0)
	v_pk_mul_f32 v[12:13], v[12:13], v[16:17] op_sel_hi:[1,0]
	v_add_u32_e32 v18, 0xb0, v146
	v_ashrrev_i32_e32 v19, 31, v18
	v_lshlrev_b64 v[18:19], 12, v[18:19]
	v_lshl_add_u64 v[18:19], s[30:31], 0, v[18:19]
	v_pk_mul_f32 v[14:15], v[14:15], v[16:17] op_sel_hi:[1,0]
	v_pk_mul_f32 v[8:9], v[8:9], v[16:17] op_sel_hi:[1,0]
	v_pk_mul_f32 v[10:11], v[10:11], v[16:17] op_sel_hi:[1,0]
	v_pk_mul_f32 v[4:5], v[4:5], v[16:17] op_sel_hi:[1,0]
	v_pk_mul_f32 v[6:7], v[6:7], v[16:17] op_sel_hi:[1,0]
	v_pk_mul_f32 v[0:1], v[0:1], v[16:17] op_sel_hi:[1,0]
	v_pk_mul_f32 v[2:3], v[2:3], v[16:17] op_sel_hi:[1,0]
	v_lshl_add_u64 v[18:19], v[18:19], 0, v[144:145]
	v_pk_mul_f32 v[14:15], v[142:143], v[14:15]
	v_pk_mul_f32 v[12:13], v[140:141], v[12:13]
	v_pk_mul_f32 v[10:11], v[138:139], v[10:11]
	v_pk_mul_f32 v[8:9], v[136:137], v[8:9]
	v_pk_mul_f32 v[6:7], v[134:135], v[6:7]
	v_pk_mul_f32 v[4:5], v[132:133], v[4:5]
	v_pk_mul_f32 v[2:3], v[130:131], v[2:3]
	v_pk_mul_f32 v[0:1], v[128:129], v[0:1]
	global_store_dwordx4 v[18:19], v[12:15], off sc1
	global_store_dwordx4 v[18:19], v[8:11], off offset:64 sc1
	global_store_dwordx4 v[18:19], v[4:7], off offset:512 sc1
	global_store_dwordx4 v[18:19], v[0:3], off offset:576 sc1

; __device__ __forceinline__ void pass_final(float* xo, const float* ssq, const float* g) {
;     const int lane = threadIdx.x & 63, gw = blockIdx.x * NWAVES + (threadIdx.x >> 6), NGW = gridDim.x * NWAVES;
;     for (int row = gw; row < NTOK; row += NGW) {
;         f32x4* xr = (f32x4*)(xo + (size_t)row * DM) + lane;
;         float s = ssq[(size_t)row * 16 + (lane & 15)]; s += __shfl_xor(s, 1); s += __shfl_xor(s, 2); s += __shfl_xor(s, 4); s += __shfl_xor(s, 8);
;         const float rstd = 1.0f / sqrtf(s * (1.0f / DM) + EPS);
;         const f32x4* g4 = (const f32x4*)g + lane;
; #pragma unroll
;         for (int j = 0; j < 4; ++j) { const f32x4 v = xr[64 * j]; xr[64 * j] = v * rstd * g4[64 * j]; }
;     }
.LBB0_1216:
	global_load_dword v13, v[4:5], off
	global_load_dwordx4 v[14:17], v[6:7], off offset:-3072
	global_load_dwordx4 v[18:21], v[2:3], off
	global_load_dwordx4 v[22:25], v[6:7], off offset:-2048
	v_add_u32_e32 v0, s2, v0
	v_lshl_add_u64 v[4:5], v[4:5], 0, s[4:5]
	s_waitcnt vmcnt(0)
	ds_bpermute_b32 v26, v8, v13
	s_waitcnt lgkmcnt(0)
	v_add_f32_e32 v13, v13, v26
	ds_bpermute_b32 v26, v9, v13
	s_waitcnt lgkmcnt(0)
	v_add_f32_e32 v13, v13, v26
	ds_bpermute_b32 v26, v10, v13
	s_waitcnt lgkmcnt(0)
	v_add_f32_e32 v13, v13, v26
	ds_bpermute_b32 v26, v11, v13
	s_waitcnt lgkmcnt(0)
	v_add_f32_e32 v13, v13, v26
	v_fmamk_f32 v13, v13, 0x3a800000, v1
	v_mul_f32_e32 v26, 0x4f800000, v13
	v_cmp_gt_f32_e32 vcc, s3, v13
	s_nop 1
	v_cndmask_b32_e32 v13, v13, v26, vcc
	v_sqrt_f32_e32 v26, v13
	s_nop 0
	v_add_u32_e32 v27, -1, v26
	v_add_u32_e32 v28, 1, v26
	v_fma_f32 v29, -v27, v26, v13
	v_fma_f32 v30, -v28, v26, v13
	v_cmp_ge_f32_e64 s[0:1], 0, v29
	s_nop 1
	v_cndmask_b32_e64 v26, v26, v27, s[0:1]
	v_cmp_lt_f32_e64 s[0:1], 0, v30
	s_nop 1
	v_cndmask_b32_e64 v26, v26, v28, s[0:1]
	v_mul_f32_e32 v27, 0x37800000, v26
	v_cndmask_b32_e32 v26, v26, v27, vcc
	v_cmp_class_f32_e32 vcc, v13, v12
	s_nop 1
	v_cndmask_b32_e32 v13, v26, v13, vcc
	v_div_scale_f32 v26, s[0:1], v13, v13, 1.0
	v_rcp_f32_e32 v28, v26
	v_div_scale_f32 v27, vcc, 1.0, v13, 1.0
	v_fma_f32 v29, -v26, v28, 1.0
	v_fmac_f32_e32 v28, v29, v28
	v_mul_f32_e32 v29, v27, v28
	v_fma_f32 v30, -v26, v29, v27
	v_fmac_f32_e32 v29, v30, v28
	v_fma_f32 v26, -v26, v29, v27
	v_div_fmas_f32 v26, v26, v28, v29
	v_div_fixup_f32 v26, v26, v13, 1.0
	v_pk_mul_f32 v[14:15], v[14:15], v[26:27] op_sel_hi:[1,0]
	v_pk_mul_f32 v[16:17], v[16:17], v[26:27] op_sel_hi:[1,0]
	v_pk_mul_f32 v[14:15], v[18:19], v[14:15]
	v_pk_mul_f32 v[16:17], v[20:21], v[16:17]
	global_store_dwordx4 v[6:7], v[14:17], off offset:-3072 sc1
	global_load_dwordx4 v[14:17], v[2:3], off offset:1024
	s_nop 0
	global_load_dwordx4 v[18:21], v[6:7], off offset:-1024
	v_pk_mul_f32 v[24:25], v[24:25], v[26:27] op_sel_hi:[1,0]
	v_pk_mul_f32 v[22:23], v[22:23], v[26:27] op_sel_hi:[1,0]
	v_cmp_lt_i32_e32 vcc, s10, v0
	s_or_b64 s[8:9], vcc, s[8:9]
	s_waitcnt vmcnt(1)
	v_pk_mul_f32 v[14:15], v[14:15], v[22:23]
	v_pk_mul_f32 v[16:17], v[16:17], v[24:25]
	global_store_dwordx4 v[6:7], v[14:17], off offset:-2048 sc1
	global_load_dwordx4 v[14:17], v[2:3], off offset:2048
	s_nop 0
	global_load_dwordx4 v[22:25], v[6:7], off
	s_waitcnt vmcnt(3)
	v_pk_mul_f32 v[20:21], v[20:21], v[26:27] op_sel_hi:[1,0]
	v_pk_mul_f32 v[18:19], v[18:19], v[26:27] op_sel_hi:[1,0]
	s_waitcnt vmcnt(1)
	v_pk_mul_f32 v[16:17], v[16:17], v[20:21]
	v_pk_mul_f32 v[14:15], v[14:15], v[18:19]
	global_store_dwordx4 v[6:7], v[14:17], off offset:-1024 sc1
	global_load_dwordx4 v[14:17], v[2:3], off offset:3072
	s_waitcnt vmcnt(2)
	v_pk_mul_f32 v[18:19], v[26:27], v[24:25] op_sel_hi:[0,1]
	v_pk_mul_f32 v[20:21], v[26:27], v[22:23] op_sel_hi:[0,1]
	s_waitcnt vmcnt(0)
	v_pk_mul_f32 v[14:15], v[20:21], v[14:15]
	v_pk_mul_f32 v[16:17], v[18:19], v[16:17]
	global_store_dwordx4 v[6:7], v[14:17], off sc1
	v_lshl_add_u64 v[6:7], v[6:7], 0, s[6:7]
	s_andn2_b64 exec, exec, s[8:9]
	s_cbranch_execnz .LBB0_1216
